# nt on the read-once row loads of the P6 LayerNorm loop
# speedup vs baseline: 1.0061x; 1.0018x over previous
; __device__ __forceinline__ float row16_sum(float v) { v += dpp_f<0x121>(v); v += dpp_f<0x122>(v); v += dpp_f<0x124>(v); v += dpp_f<0x128>(v); return v; }
; __device__ __forceinline__ void ln_rows(const Ptrs& P, int tid, int G) {
;     ...
;     for (int m = gw; m < M; m += 2 * NGW) {
;         const int m1 = m + NGW; const bool two = m1 < M;
;         float* y0 = P.out + (size_t)m * D + 4 * lane; float* y1 = P.out + (size_t)(two ? m1 : m) * D + 4 * lane;
;         f32x4 v[8], u[8]; float s = 0.f, t = 0.f;
; #pragma unroll
;         for (int j = 0; j < 8; ++j) { v[j] = *(const f32x4*)(y0 + 256 * j); u[j] = *(const f32x4*)(y1 + 256 * j); }
; #pragma unroll
;         for (int j = 0; j < 8; ++j) { s += (v[j][0] + v[j][1]) + (v[j][2] + v[j][3]); t += (u[j][0] + u[j][1]) + (u[j][2] + u[j][3]); }
;         s = rows4_sum(row16_sum(s)); t = rows4_sum(row16_sum(t));
;         const float mean0 = s * (1.f / D), mean1 = t * (1.f / D); float s2 = 0.f, t2 = 0.f;
; #pragma unroll
;         for (int j = 0; j < 8; ++j) { v[j] = v[j] - mean0; u[j] = u[j] - mean1;
;             s2 += (v[j][0] * v[j][0] + v[j][1] * v[j][1]) + (v[j][2] * v[j][2] + v[j][3] * v[j][3]);
;             t2 += (u[j][0] * u[j][0] + u[j][1] * u[j][1]) + (u[j][2] * u[j][2] + u[j][3] * u[j][3]); }
.LBB0_1084:
	v_ashrrev_i32_e32 v65, 31, v64
	v_lshlrev_b64 v[66:67], 13, v[64:65]
	v_lshl_add_u64 v[134:135], v[128:129], 0, v[66:67]
	v_add_u32_e32 v138, s16, v64
	global_load_dwordx4 v[124:127], v[134:135], off nt
	global_load_dwordx4 v[120:123], v[134:135], off offset:1024 nt
	global_load_dwordx4 v[116:119], v[134:135], off offset:2048 nt
	global_load_dwordx4 v[112:115], v[134:135], off offset:3072 nt
	v_add_co_u32_e32 v132, vcc, s15, v134
	v_cmp_gt_i32_e64 s[0:1], s14, v138
	s_nop 0
	v_addc_co_u32_e32 v133, vcc, 0, v135, vcc
	v_cndmask_b32_e64 v64, v64, v138, s[0:1]
	global_load_dwordx4 v[108:111], v[132:133], off nt
	global_load_dwordx4 v[104:107], v[132:133], off offset:1024 nt
	global_load_dwordx4 v[100:103], v[132:133], off offset:2048 nt
	global_load_dwordx4 v[96:99], v[132:133], off offset:3072 nt
	v_ashrrev_i32_e32 v65, 31, v64
	v_lshlrev_b64 v[64:65], 13, v[64:65]
	v_lshl_add_u64 v[130:131], v[128:129], 0, v[64:65]
	global_load_dwordx4 v[92:95], v[130:131], off nt
	global_load_dwordx4 v[88:91], v[130:131], off offset:1024 nt
	global_load_dwordx4 v[84:87], v[130:131], off offset:2048 nt
	global_load_dwordx4 v[80:83], v[130:131], off offset:3072 nt
	v_add_co_u32_e32 v64, vcc, s15, v130
	s_waitcnt vmcnt(0)
	v_add_f32_e32 v139, v124, v125
	v_addc_co_u32_e32 v65, vcc, 0, v131, vcc
	global_load_dwordx4 v[76:79], v[64:65], off nt
	global_load_dwordx4 v[72:75], v[64:65], off offset:1024 nt
	global_load_dwordx4 v[68:71], v[64:65], off offset:2048 nt
	s_nop 0
	global_load_dwordx4 v[64:67], v[64:65], off offset:3072 nt
	v_add_f32_e32 v140, v126, v127
	v_add_f32_e32 v141, v120, v121
	v_add_f32_e32 v142, v122, v123
	v_add_f32_e32 v139, v139, v140
	v_add_f32_e32 v143, v116, v117
	v_add_f32_e32 v144, v118, v119
	v_add_f32_e32 v140, v141, v142
	v_add_f32_e32 v139, 0, v139
	v_add_f32_e32 v145, v112, v113
	v_add_f32_e32 v146, v114, v115
	v_add_f32_e32 v141, v143, v144
	v_add_f32_e32 v139, v139, v140
	v_add_f32_e32 v142, v145, v146
	v_add_f32_e32 v143, v108, v109
	v_add_f32_e32 v144, v110, v111
	v_add_f32_e32 v139, v139, v141
	v_add_f32_e32 v145, v104, v105
	v_add_f32_e32 v146, v106, v107
	v_add_f32_e32 v147, v100, v101
	v_add_f32_e32 v148, v102, v103
	v_add_f32_e32 v151, v92, v93
	v_add_f32_e32 v152, v94, v95
	v_add_f32_e32 v143, v143, v144
	v_add_f32_e32 v139, v139, v142
	v_add_f32_e32 v153, v88, v89
	v_add_f32_e32 v154, v90, v91
	v_add_f32_e32 v144, v145, v146
	v_add_f32_e32 v145, v147, v148
	v_add_f32_e32 v147, v151, v152
	v_add_f32_e32 v139, v139, v143
	v_add_f32_e32 v149, v96, v97
	v_add_f32_e32 v150, v98, v99
	v_add_f32_e32 v155, v84, v85
	v_add_f32_e32 v156, v86, v87
	v_add_f32_e32 v140, v153, v154
	v_add_f32_e32 v147, 0, v147
	v_add_f32_e32 v139, v139, v144
	v_add_f32_e32 v157, v80, v81
	v_add_f32_e32 v158, v82, v83
	v_add_f32_e32 v146, v149, v150
	v_add_f32_e32 v148, v155, v156
	v_add_f32_e32 v140, v147, v140
	v_add_f32_e32 v139, v139, v145
	v_add_f32_e32 v149, v157, v158
	v_add_f32_e32 v140, v140, v148
	v_add_f32_e32 v139, v139, v146
	v_add_f32_e32 v140, v140, v149
	s_waitcnt vmcnt(3)
	v_add_f32_e32 v150, v76, v77
	v_add_f32_e32 v151, v78, v79
	s_waitcnt vmcnt(2)
	v_add_f32_e32 v152, v72, v73
	v_add_f32_e32 v153, v74, v75
	v_add_f32_e32 v141, v150, v151
	v_add_f32_dpp v139, v139, v139 row_ror:1 row_mask:0xf bank_mask:0xf bound_ctrl:1
	s_waitcnt vmcnt(1)
	v_add_f32_e32 v154, v68, v69
	v_add_f32_e32 v155, v70, v71
	v_add_f32_e32 v150, v152, v153
	v_add_f32_e32 v140, v140, v141
	v_add_f32_dpp v139, v139, v139 row_ror:2 row_mask:0xf bank_mask:0xf bound_ctrl:1
	s_waitcnt vmcnt(0)
	v_add_f32_e32 v156, v64, v65
	v_add_f32_e32 v151, v154, v155
	v_add_f32_e32 v140, v140, v150
	v_add_f32_e32 v141, v66, v67
	v_add_f32_dpp v139, v139, v139 row_ror:4 row_mask:0xf bank_mask:0xf bound_ctrl:1
	v_add_f32_e32 v140, v140, v151
	v_add_f32_e32 v141, v156, v141
	v_add_f32_dpp v139, v139, v139 row_ror:8 row_mask:0xf bank_mask:0xf bound_ctrl:1
	v_add_f32_e32 v140, v140, v141
	v_mov_b32_e32 v141, v139
	s_nop 1
	v_permlane32_swap_b32 v139, v141
	s_nop 0
	v_add_f32_dpp v140, v140, v140 row_ror:1 row_mask:0xf bank_mask:0xf bound_ctrl:1
	v_add_f32_e32 v139, v139, v141
	v_mov_b32_e32 v141, v139
	v_add_f32_dpp v140, v140, v140 row_ror:2 row_mask:0xf bank_mask:0xf bound_ctrl:1
	s_nop 1
	v_permlane16_swap_b32 v139, v141
	s_nop 0
	v_add_f32_e32 v139, v139, v141
	v_add_f32_dpp v140, v140, v140 row_ror:4 row_mask:0xf bank_mask:0xf bound_ctrl:1
	v_fmamk_f32 v126, v139, 0xba000000, v126
	v_fmac_f32_e32 v125, 0xba000000, v139
	v_add_f32_dpp v140, v140, v140 row_ror:8 row_mask:0xf bank_mask:0xf bound_ctrl:1
	v_mov_b32_e32 v141, v140
	s_nop 1
	v_permlane32_swap_b32 v140, v141
	v_fmamk_f32 v127, v139, 0xba000000, v127
	v_add_f32_e32 v140, v140, v141
	v_mov_b32_e32 v141, v140
	s_nop 1
	v_permlane16_swap_b32 v140, v141
	v_fmamk_f32 v124, v139, 0xba000000, v124
	v_add_f32_e32 v150, v140, v141
	v_mul_f32_e32 v140, v125, v125
	v_mul_f32_e32 v141, v126, v126
	v_fmamk_f32 v95, v150, 0xba000000, v95
	v_fmamk_f32 v93, v150, 0xba000000, v93
	v_fmac_f32_e32 v140, v124, v124
	v_fmac_f32_e32 v141, v127, v127
	v_fmamk_f32 v94, v150, 0xba000000, v94
	v_fmac_f32_e32 v92, 0xba000000, v150
	v_add_f32_e32 v140, v140, v141
	v_mul_f32_e32 v141, v93, v93
	v_mul_f32_e32 v142, v95, v95
	v_fmac_f32_e32 v141, v92, v92
	v_fmac_f32_e32 v142, v94, v94
	v_fmamk_f32 v122, v139, 0xba000000, v122
	v_fmac_f32_e32 v121, 0xba000000, v139
	v_add_f32_e32 v141, v141, v142
	v_fmamk_f32 v123, v139, 0xba000000, v123
	v_fmamk_f32 v120, v139, 0xba000000, v120
	v_mul_f32_e32 v142, v121, v121
	v_mul_f32_e32 v143, v122, v122
	v_fmac_f32_e32 v142, v120, v120
	v_fmac_f32_e32 v143, v123, v123
	v_fmamk_f32 v91, v150, 0xba000000, v91
; __device__ __forceinline__ float row16_sum(float v) { v += dpp_f<0x121>(v); v += dpp_f<0x122>(v); v += dpp_f<0x124>(v); v += dpp_f<0x128>(v); return v; }
; __device__ __forceinline__ void ln_rows(const Ptrs& P, int tid, int G) {
;     ...
;         for (int j = 0; j < 8; ++j) { v[j] = v[j] - mean0; u[j] = u[j] - mean1;
;             s2 += (v[j][0] * v[j][0] + v[j][1] * v[j][1]) + (v[j][2] * v[j][2] + v[j][3] * v[j][3]);
;             t2 += (u[j][0] * u[j][0] + u[j][1] * u[j][1]) + (u[j][2] * u[j][2] + u[j][3] * u[j][3]); }
;         s2 = rows4_sum(row16_sum(s2)); t2 = rows4_sum(row16_sum(t2));
;         const float rstd0 = 1.f / sqrtf(s2 * (1.f / D) + LN_EPS), rstd1 = 1.f / sqrtf(t2 * (1.f / D) + LN_EPS);
	v_fmamk_f32 v89, v150, 0xba000000, v89
	v_add_f32_e32 v142, v142, v143
	v_fmamk_f32 v90, v150, 0xba000000, v90
	v_fmac_f32_e32 v88, 0xba000000, v150
	v_add_f32_e32 v140, v140, v142
	v_mul_f32_e32 v142, v89, v89
	v_mul_f32_e32 v143, v91, v91
	v_fmac_f32_e32 v142, v88, v88
	v_fmac_f32_e32 v143, v90, v90
	v_add_f32_e32 v142, v142, v143
	v_fmamk_f32 v118, v139, 0xba000000, v118
	v_fmac_f32_e32 v117, 0xba000000, v139
	v_add_f32_e32 v141, v141, v142
	v_fmamk_f32 v119, v139, 0xba000000, v119
	v_fmamk_f32 v116, v139, 0xba000000, v116
	v_mul_f32_e32 v142, v117, v117
	v_mul_f32_e32 v143, v118, v118
	v_fmac_f32_e32 v142, v116, v116
	v_fmac_f32_e32 v143, v119, v119
	v_fmamk_f32 v87, v150, 0xba000000, v87
	v_fmamk_f32 v85, v150, 0xba000000, v85
	v_add_f32_e32 v142, v142, v143
	v_fmamk_f32 v86, v150, 0xba000000, v86
	v_fmac_f32_e32 v84, 0xba000000, v150
	v_add_f32_e32 v142, v142, v140
	v_mul_f32_e32 v140, v85, v85
	v_mul_f32_e32 v143, v87, v87
	v_fmac_f32_e32 v140, v84, v84
	v_fmac_f32_e32 v143, v86, v86
	v_add_f32_e32 v140, v140, v143
	v_add_f32_e32 v143, v140, v141
	v_fmamk_f32 v140, v139, 0xba000000, v114
	v_fmac_f32_e32 v113, 0xba000000, v139
	v_fmamk_f32 v141, v139, 0xba000000, v115
	v_fmamk_f32 v112, v139, 0xba000000, v112
	v_mul_f32_e32 v114, v113, v113
	v_mul_f32_e32 v115, v140, v140
	v_fmac_f32_e32 v114, v112, v112
	v_fmac_f32_e32 v115, v141, v141
	v_fmamk_f32 v83, v150, 0xba000000, v83
	v_fmamk_f32 v81, v150, 0xba000000, v81
	v_add_f32_e32 v114, v114, v115
	v_fmamk_f32 v82, v150, 0xba000000, v82
	v_fmac_f32_e32 v80, 0xba000000, v150
	v_add_f32_e32 v114, v114, v142
	v_mul_f32_e32 v115, v81, v81
	v_mul_f32_e32 v142, v83, v83
	v_fmac_f32_e32 v115, v80, v80
	v_fmac_f32_e32 v142, v82, v82
	v_add_f32_e32 v115, v115, v142
	v_fmamk_f32 v142, v139, 0xba000000, v110
	v_fmac_f32_e32 v109, 0xba000000, v139
	v_add_f32_e32 v115, v115, v143
	v_fmamk_f32 v143, v139, 0xba000000, v111
	v_fmamk_f32 v108, v139, 0xba000000, v108
	v_mul_f32_e32 v110, v109, v109
	v_mul_f32_e32 v111, v142, v142
	v_fmamk_f32 v144, v139, 0xba000000, v106
	v_fmac_f32_e32 v105, 0xba000000, v139
	v_fmac_f32_e32 v110, v108, v108
	v_fmac_f32_e32 v111, v143, v143
	v_fmamk_f32 v145, v139, 0xba000000, v107
	v_fmamk_f32 v104, v139, 0xba000000, v104
	v_mul_f32_e32 v106, v105, v105
	v_mul_f32_e32 v107, v144, v144
	v_fmamk_f32 v146, v139, 0xba000000, v102
	v_fmac_f32_e32 v101, 0xba000000, v139
	v_add_f32_e32 v110, v110, v111
	v_fmac_f32_e32 v106, v104, v104
	v_fmac_f32_e32 v107, v145, v145
	v_fmamk_f32 v147, v139, 0xba000000, v103
	v_fmamk_f32 v100, v139, 0xba000000, v100
	v_mul_f32_e32 v102, v101, v101
	v_mul_f32_e32 v103, v146, v146
	v_fmamk_f32 v148, v139, 0xba000000, v98
	v_fmac_f32_e32 v97, 0xba000000, v139
	v_add_f32_e32 v110, v110, v114
	v_add_f32_e32 v106, v106, v107
	v_fmac_f32_e32 v102, v100, v100
	v_fmac_f32_e32 v103, v147, v147
	v_fmamk_f32 v149, v139, 0xba000000, v99
	v_fmamk_f32 v96, v139, 0xba000000, v96
	v_mul_f32_e32 v98, v97, v97
	v_mul_f32_e32 v99, v148, v148
	v_add_f32_e32 v106, v106, v110
	v_add_f32_e32 v102, v102, v103
	v_fmac_f32_e32 v98, v96, v96
	v_fmac_f32_e32 v99, v149, v149
	v_add_f32_e32 v102, v102, v106
	v_add_f32_e32 v98, v98, v99
	v_add_f32_e32 v98, v98, v102
	v_fmamk_f32 v67, v150, 0xba000000, v67
	v_fmamk_f32 v65, v150, 0xba000000, v65
	v_add_f32_dpp v98, v98, v98 row_ror:1 row_mask:0xf bank_mask:0xf bound_ctrl:1
	v_fmamk_f32 v66, v150, 0xba000000, v66
	v_fmac_f32_e32 v64, 0xba000000, v150
	v_add_f32_dpp v98, v98, v98 row_ror:2 row_mask:0xf bank_mask:0xf bound_ctrl:1
	v_mul_f32_e32 v99, v65, v65
	v_mul_f32_e32 v102, v67, v67
	v_add_f32_dpp v98, v98, v98 row_ror:4 row_mask:0xf bank_mask:0xf bound_ctrl:1
	v_fmac_f32_e32 v99, v64, v64
	v_fmac_f32_e32 v102, v66, v66
	v_add_f32_dpp v98, v98, v98 row_ror:8 row_mask:0xf bank_mask:0xf bound_ctrl:1
	v_add_f32_e32 v99, v99, v102
	v_mov_b32_e32 v102, v98
	s_nop 1
	v_permlane32_swap_b32 v98, v102
	v_fmamk_f32 v79, v150, 0xba000000, v79
	v_add_f32_e32 v98, v98, v102
	v_mov_b32_e32 v102, v98
	s_nop 1
	v_permlane16_swap_b32 v98, v102
	v_fmamk_f32 v77, v150, 0xba000000, v77
	v_add_f32_e32 v98, v98, v102
	v_fmamk_f32 v98, v98, 0x3a000000, v136
	v_mul_f32_e32 v102, 0x4f800000, v98
	v_cmp_gt_f32_e32 vcc, s17, v98
	v_fmamk_f32 v78, v150, 0xba000000, v78
	v_fmac_f32_e32 v76, 0xba000000, v150
	v_cndmask_b32_e32 v98, v98, v102, vcc
	v_mul_f32_e32 v111, v77, v77
	v_mul_f32_e32 v114, v79, v79
	v_fmamk_f32 v75, v150, 0xba000000, v75
	v_fmamk_f32 v73, v150, 0xba000000, v73
	v_sqrt_f32_e32 v102, v98
	v_fmac_f32_e32 v111, v76, v76
	v_fmac_f32_e32 v114, v78, v78
	v_fmamk_f32 v74, v150, 0xba000000, v74
	v_fmac_f32_e32 v72, 0xba000000, v150
	v_mul_f32_e32 v107, v73, v73
	v_mul_f32_e32 v110, v75, v75
	v_fmamk_f32 v71, v150, 0xba000000, v71
	v_fmamk_f32 v69, v150, 0xba000000, v69
	v_add_f32_e32 v111, v111, v114
	v_fmac_f32_e32 v107, v72, v72
	v_fmac_f32_e32 v110, v74, v74
	v_fmamk_f32 v70, v150, 0xba000000, v70
	v_fmac_f32_e32 v68, 0xba000000, v150
	v_mul_f32_e32 v103, v69, v69
	v_mul_f32_e32 v106, v71, v71
	v_add_f32_e32 v111, v111, v115
	v_add_f32_e32 v107, v107, v110
	v_fmac_f32_e32 v103, v68, v68
	v_fmac_f32_e32 v106, v70, v70
	v_add_f32_e32 v107, v107, v111
	v_add_f32_e32 v103, v103, v106
	v_add_u32_e32 v106, -1, v102
	v_add_f32_e32 v103, v103, v107
	v_fma_f32 v107, -v106, v102, v98
	v_cmp_ge_f32_e64 s[2:3], 0, v107
	v_add_u32_e32 v107, 1, v102
	v_add_f32_e32 v99, v99, v103
	v_cndmask_b32_e64 v106, v102, v106, s[2:3]
	v_fma_f32 v102, -v107, v102, v98
	v_cmp_lt_f32_e64 s[2:3], 0, v102
	v_add_f32_dpp v99, v99, v99 row_ror:1 row_mask:0xf bank_mask:0xf bound_ctrl:1
	s_nop 0
	v_cndmask_b32_e64 v102, v106, v107, s[2:3]
	v_mul_f32_e32 v106, 0x37800000, v102
; __device__ __forceinline__ void ln_rows(const Ptrs& P, int tid, int G) {
;     ...
;         const float rstd0 = 1.f / sqrtf(s2 * (1.f / D) + LN_EPS), rstd1 = 1.f / sqrtf(t2 * (1.f / D) + LN_EPS);
; #pragma unroll
;         for (int j = 0; j < 8; ++j) *(f32x4*)(y0 + 256 * j) = v[j] * rstd0 * gg[j] + bb[j];
;         if (two) {
; #pragma unroll
;             for (int j = 0; j < 8; ++j) *(f32x4*)(y1 + 256 * j) = u[j] * rstd1 * gg[j] + bb[j]; }
;     }
	v_cndmask_b32_e32 v102, v102, v106, vcc
	v_cmp_class_f32_e32 vcc, v98, v137
	v_add_f32_dpp v99, v99, v99 row_ror:2 row_mask:0xf bank_mask:0xf bound_ctrl:1
	s_nop 0
	v_cndmask_b32_e32 v102, v102, v98, vcc
	v_div_scale_f32 v106, s[2:3], v102, v102, 1.0
	v_add_f32_dpp v99, v99, v99 row_ror:4 row_mask:0xf bank_mask:0xf bound_ctrl:1
	v_rcp_f32_e32 v107, v106
	s_nop 0
	v_add_f32_dpp v99, v99, v99 row_ror:8 row_mask:0xf bank_mask:0xf bound_ctrl:1
	v_mov_b32_e32 v103, v99
	s_nop 1
	v_permlane32_swap_b32 v99, v103
	s_nop 0
	v_add_f32_e32 v98, v99, v103
	v_fma_f32 v103, -v106, v107, 1.0
	v_fmac_f32_e32 v107, v103, v107
	v_div_scale_f32 v103, vcc, 1.0, v102, 1.0
	v_mul_f32_e32 v110, v103, v107
	v_fma_f32 v111, -v106, v110, v103
	v_fmac_f32_e32 v110, v111, v107
	v_fma_f32 v103, -v106, v110, v103
	v_div_fmas_f32 v103, v103, v107, v110
	v_div_fixup_f32 v150, v103, v102, 1.0
	v_pk_mul_f32 v[102:103], v[124:125], v[150:151] op_sel_hi:[1,0]
	v_pk_mul_f32 v[106:107], v[126:127], v[150:151] op_sel_hi:[1,0]
	v_pk_fma_f32 v[124:125], v[0:1], v[102:103], v[8:9]
	v_pk_fma_f32 v[126:127], v[2:3], v[106:107], v[10:11]
	v_pk_mul_f32 v[102:103], v[120:121], v[150:151] op_sel_hi:[1,0]
	v_pk_mul_f32 v[106:107], v[122:123], v[150:151] op_sel_hi:[1,0]
	v_pk_fma_f32 v[120:121], v[4:5], v[102:103], v[12:13]
	v_pk_fma_f32 v[122:123], v[6:7], v[106:107], v[14:15]
	v_pk_mul_f32 v[102:103], v[116:117], v[150:151] op_sel_hi:[1,0]
	v_pk_mul_f32 v[106:107], v[118:119], v[150:151] op_sel_hi:[1,0]
	v_pk_fma_f32 v[114:115], v[16:17], v[102:103], v[24:25]
	v_pk_fma_f32 v[116:117], v[18:19], v[106:107], v[26:27]
	v_pk_mul_f32 v[102:103], v[112:113], v[150:151] op_sel_hi:[1,0]
	v_pk_mul_f32 v[106:107], v[140:141], v[150:151] op_sel_hi:[1,0]
	v_pk_fma_f32 v[110:111], v[20:21], v[102:103], v[28:29]
	v_pk_fma_f32 v[112:113], v[22:23], v[106:107], v[30:31]
	v_pk_mul_f32 v[102:103], v[108:109], v[150:151] op_sel_hi:[1,0]
	v_pk_mul_f32 v[106:107], v[142:143], v[150:151] op_sel_hi:[1,0]
	v_pk_mul_f32 v[100:101], v[100:101], v[150:151] op_sel_hi:[1,0]
	v_pk_fma_f32 v[108:109], v[34:35], v[106:107], v[42:43]
	v_pk_fma_f32 v[106:107], v[32:33], v[102:103], v[40:41]
	v_pk_mul_f32 v[102:103], v[104:105], v[150:151] op_sel_hi:[1,0]
	v_pk_mul_f32 v[104:105], v[144:145], v[150:151] op_sel_hi:[1,0]
	v_pk_fma_f32 v[102:103], v[36:37], v[102:103], v[44:45]
	v_pk_fma_f32 v[104:105], v[38:39], v[104:105], v[46:47]
	global_store_dwordx4 v[132:133], v[102:105], off offset:1024
	v_pk_fma_f32 v[100:101], v[48:49], v[100:101], v[56:57]
	v_pk_mul_f32 v[96:97], v[96:97], v[150:151] op_sel_hi:[1,0]
	v_pk_mul_f32 v[102:103], v[146:147], v[150:151] op_sel_hi:[1,0]
	v_mov_b32_e32 v99, v98
	v_pk_fma_f32 v[102:103], v[50:51], v[102:103], v[58:59]
	global_store_dwordx4 v[132:133], v[100:103], off offset:2048
	s_nop 1
	v_permlane16_swap_b32 v98, v99
	global_store_dwordx4 v[134:135], v[124:127], off
	global_store_dwordx4 v[134:135], v[120:123], off offset:1024
	v_pk_mul_f32 v[100:101], v[148:149], v[150:151] op_sel_hi:[1,0]
	global_store_dwordx4 v[134:135], v[114:117], off offset:2048
	v_pk_fma_f32 v[102:103], v[54:55], v[100:101], v[62:63]
	v_pk_fma_f32 v[100:101], v[52:53], v[96:97], v[60:61]
	global_store_dwordx4 v[134:135], v[110:113], off offset:3072
	global_store_dwordx4 v[132:133], v[106:109], off
	global_store_dwordx4 v[132:133], v[100:103], off offset:3072
	s_and_saveexec_b64 s[2:3], s[0:1]
	s_cbranch_execz .LBB0_1083
	v_add_f32_e32 v96, v98, v99
	v_fmamk_f32 v96, v96, 0x3a000000, v136
	v_mul_f32_e32 v97, 0x4f800000, v96
	v_cmp_gt_f32_e32 vcc, s17, v96
	v_lshl_add_u64 v[102:103], v[130:131], 0, s[12:13]
	s_nop 0
	v_cndmask_b32_e32 v98, v96, v97, vcc
	v_sqrt_f32_e32 v99, v98
	v_lshl_add_u64 v[96:97], v[130:131], 0, s[6:7]
	v_add_u32_e32 v100, -1, v99
	v_fma_f32 v101, -v100, v99, v98
	v_cmp_ge_f32_e64 s[0:1], 0, v101
	v_add_u32_e32 v101, 1, v99
	s_nop 0
	v_cndmask_b32_e64 v100, v99, v100, s[0:1]
	v_fma_f32 v99, -v101, v99, v98
	v_cmp_lt_f32_e64 s[0:1], 0, v99
	s_nop 1
	v_cndmask_b32_e64 v99, v100, v101, s[0:1]
	v_mul_f32_e32 v100, 0x37800000, v99
	v_cndmask_b32_e32 v99, v99, v100, vcc
	v_cmp_class_f32_e32 vcc, v98, v137
	v_lshl_add_u64 v[100:101], v[130:131], 0, s[10:11]
	s_nop 0
	v_cndmask_b32_e32 v104, v99, v98, vcc
	v_div_scale_f32 v105, s[0:1], v104, v104, 1.0
	v_rcp_f32_e32 v106, v105
	v_lshl_add_u64 v[98:99], v[130:131], 0, s[8:9]
	v_fma_f32 v107, -v105, v106, 1.0
	v_fmac_f32_e32 v106, v107, v106
	v_div_scale_f32 v107, vcc, 1.0, v104, 1.0
	v_mul_f32_e32 v108, v107, v106
	v_fma_f32 v109, -v105, v108, v107
	v_fmac_f32_e32 v108, v109, v106
	v_fma_f32 v105, -v105, v108, v107
	v_div_fmas_f32 v105, v105, v106, v108
	v_div_fixup_f32 v104, v105, v104, 1.0
	v_pk_mul_f32 v[92:93], v[92:93], v[104:105] op_sel_hi:[1,0]
	v_pk_mul_f32 v[94:95], v[94:95], v[104:105] op_sel_hi:[1,0]
	v_pk_mul_f32 v[88:89], v[88:89], v[104:105] op_sel_hi:[1,0]
	v_pk_mul_f32 v[90:91], v[90:91], v[104:105] op_sel_hi:[1,0]
	v_pk_mul_f32 v[84:85], v[84:85], v[104:105] op_sel_hi:[1,0]
	v_pk_mul_f32 v[86:87], v[86:87], v[104:105] op_sel_hi:[1,0]
	v_pk_mul_f32 v[80:81], v[80:81], v[104:105] op_sel_hi:[1,0]
	v_pk_mul_f32 v[82:83], v[82:83], v[104:105] op_sel_hi:[1,0]
	v_pk_mul_f32 v[76:77], v[76:77], v[104:105] op_sel_hi:[1,0]
	v_pk_mul_f32 v[78:79], v[78:79], v[104:105] op_sel_hi:[1,0]
	v_pk_mul_f32 v[72:73], v[72:73], v[104:105] op_sel_hi:[1,0]
	v_pk_mul_f32 v[74:75], v[74:75], v[104:105] op_sel_hi:[1,0]
	v_pk_mul_f32 v[68:69], v[68:69], v[104:105] op_sel_hi:[1,0]
	v_pk_mul_f32 v[70:71], v[70:71], v[104:105] op_sel_hi:[1,0]
	v_pk_mul_f32 v[64:65], v[64:65], v[104:105] op_sel_hi:[1,0]
	v_pk_mul_f32 v[66:67], v[66:67], v[104:105] op_sel_hi:[1,0]
	v_pk_fma_f32 v[94:95], v[2:3], v[94:95], v[10:11]
	v_pk_fma_f32 v[92:93], v[0:1], v[92:93], v[8:9]
	v_pk_fma_f32 v[90:91], v[6:7], v[90:91], v[14:15]
	v_pk_fma_f32 v[88:89], v[4:5], v[88:89], v[12:13]
	v_pk_fma_f32 v[86:87], v[18:19], v[86:87], v[26:27]
	v_pk_fma_f32 v[84:85], v[16:17], v[84:85], v[24:25]
	v_pk_fma_f32 v[82:83], v[22:23], v[82:83], v[30:31]
	v_pk_fma_f32 v[80:81], v[20:21], v[80:81], v[28:29]
	v_pk_fma_f32 v[78:79], v[34:35], v[78:79], v[42:43]
	v_pk_fma_f32 v[76:77], v[32:33], v[76:77], v[40:41]
	v_pk_fma_f32 v[74:75], v[38:39], v[74:75], v[46:47]
	v_pk_fma_f32 v[72:73], v[36:37], v[72:73], v[44:45]
	v_pk_fma_f32 v[70:71], v[50:51], v[70:71], v[58:59]
	v_pk_fma_f32 v[68:69], v[48:49], v[68:69], v[56:57]
	v_pk_fma_f32 v[66:67], v[54:55], v[66:67], v[62:63]
	v_pk_fma_f32 v[64:65], v[52:53], v[64:65], v[60:61]
	global_store_dwordx4 v[130:131], v[92:95], off
	global_store_dwordx4 v[130:131], v[88:91], off offset:1024
	global_store_dwordx4 v[130:131], v[84:87], off offset:2048
	global_store_dwordx4 v[130:131], v[80:83], off offset:3072
	global_store_dwordx4 v[96:97], v[76:79], off
	global_store_dwordx4 v[98:99], v[72:75], off
	global_store_dwordx4 v[100:101], v[68:71], off
	global_store_dwordx4 v[102:103], v[64:67], off
	s_branch .LBB0_1083
